# HGRN2 output phase B: rebuilt read-ahead block used for items that carry no RG item (registers free), hipcc's block otherwise
# baseline (speedup 1.0000x reference)
.LBB0_107:
	s_cmp_eq_u32 s100, -1
	s_cbranch_scc1 .Lhg_fast
	ds_read_b128 v[86:89], v139 offset:32
	ds_read_b128 v[82:85], v139 offset:64
	ds_read_b128 v[78:81], v139 offset:96
	ds_read_b128 v[90:93], v139
	ds_read_b128 v[2:5], v130 offset:36864
	v_cndmask_b32_e64 v6, 0, 1, s[72:73]
	v_cmp_ne_u32_e64 s[52:53], 1, v6
	s_mov_b32 s86, 0x800000
	s_waitcnt lgkmcnt(1)
	v_mov_b64_e32 v[6:7], v[90:91]
	s_mov_b32 s87, 0x9000
	s_mov_b64 s[62:63], -1
	s_andn2_b64 vcc, exec, s[72:73]
	v_mov_b64_e32 v[8:9], v[92:93]
	s_cbranch_vccnz .LBB0_109
	ds_read_b128 v[6:9], v131 offset:18432
	s_mov_b64 s[62:63], 0
